# prep_gla<64> (GLA prompt) first loop: the 8 (q,k) element load pairs hoisted ahead of the per-element blocks
# baseline (speedup 1.0000x reference)
; DI float sigm(float x) { return __builtin_amdgcn_rcpf(1.f + __expf(-x)); }
; DI float softplus_(float x) { return fmaxf(x, 0.f) + log1pf(__expf(-fabsf(x))); }
; template <int K, bool HG>
; DI void prep_gla(LAS unsigned char* lds, const Params& P, int l, int unit) {
;     ...
;     for (int i = 0; i < NE; ++i) { const int t = t0 + TS * i; qv[i] = 0.f; kv[i] = 0.f; float lg = 0.f;
;         if (t < up.nvalid) { const size_t row = (size_t)(up.row0 + t);
;             if (HG) { const int ch = up.h * 128 + k; const float fp = P32[row * LDP + C_BF + ch]; qv[i] = P32[row * LDP + C_BQ + ch];
;                 const float f = lb + (1.f - lb) * sigm(fp); lg = __logf(fmaxf(f, 1e-30f)); kv[i] = (1.f - lb) * sigm(-fp); }
;             else { const int ch = up.h * 64 + k; qv[i] = P32[row * LDP + C_CQ + ch] * 0.125f; kv[i] = P32[row * LDP + C_CK + ch]; float x = bias;
; #pragma unroll
;                 for (int rr = 0; rr < 16; ++rr) x += cl[t * 16 + rr] * wcol[rr];
;                 lg = -softplus_(-x) * (1.f / 16.f); } }
;         if (t < TR) Gs[t * K + k] = lg; }
.LBB0_594:
	s_or_b64 exec, exec, s[46:47]
	s_add_u32 s64, s92, s44
	v_mov_b32_e32 v3, 0
	v_ashrrev_i32_e32 v21, 6, v6
	s_addc_u32 s65, s93, s45
	v_cmp_gt_i32_e64 s[44:45], s88, v18
	v_mov_b32_e32 v2, 0
	v_mov_b32_e32 v0, v3
	s_waitcnt lgkmcnt(0)
	s_barrier
	s_mul_i32 s7, s3, 0x6800
	s_add_u32 s8, s64, s7
	s_addc_u32 s9, s65, 0
	s_add_u32 s8, s8, 0x3000
	s_addc_u32 s9, s9, 0
	v_mul_u32_u24_e32 v122, 0x6800, v21
	v_lshl_add_u32 v122, v22, 2, v122
	global_load_dword v74, v122, s[8:9]
	global_load_dword v75, v122, s[8:9] offset:1024
	s_add_u32 s8, s8, 0x34000
	s_addc_u32 s9, s9, 0
	global_load_dword v76, v122, s[8:9]
	global_load_dword v77, v122, s[8:9] offset:1024
	s_add_u32 s8, s8, 0x34000
	s_addc_u32 s9, s9, 0
	global_load_dword v78, v122, s[8:9]
	global_load_dword v79, v122, s[8:9] offset:1024
	s_add_u32 s8, s8, 0x34000
	s_addc_u32 s9, s9, 0
	global_load_dword v80, v122, s[8:9]
	global_load_dword v81, v122, s[8:9] offset:1024
	s_add_u32 s8, s8, 0x34000
	s_addc_u32 s9, s9, 0
	global_load_dword v82, v122, s[8:9]
	global_load_dword v83, v122, s[8:9] offset:1024
	s_add_u32 s8, s8, 0x34000
	s_addc_u32 s9, s9, 0
	global_load_dword v84, v122, s[8:9]
	global_load_dword v85, v122, s[8:9] offset:1024
	s_add_u32 s8, s8, 0x34000
	s_addc_u32 s9, s9, 0
	global_load_dword v86, v122, s[8:9]
	global_load_dword v87, v122, s[8:9] offset:1024
	s_add_u32 s8, s8, 0x34000
	s_addc_u32 s9, s9, 0
	global_load_dword v88, v122, s[8:9]
	global_load_dword v89, v122, s[8:9] offset:1024
	s_and_saveexec_b64 s[46:47], s[44:45]
	s_cbranch_execz .LBB0_596
	v_add_u32_e32 v0, s3, v21
	v_mov_b64_e32 v[2:3], s[64:65]
	v_mad_i64_i32 v[2:3], s[6:7], v0, s76, v[2:3]
	v_lshl_add_u64 v[2:3], v[22:23], 2, v[2:3]
	v_add_co_u32_e32 v2, vcc, 0x3000, v2
	s_mov_b32 s5, 0xbfb8aa3b
	s_nop 0
	v_addc_co_u32_e32 v3, vcc, 0, v3, vcc
	s_waitcnt vmcnt(0)
	v_mov_b32_e32 v0, v74
	s_mov_b32 s6, 0x3f317218
	v_mov_b32_e32 v2, v75
	v_lshl_add_u32 v3, v21, 6, 0
	ds_read_b128 v[4:7], v3 offset:34816
	ds_read_b128 v[8:11], v3 offset:34832
	ds_read_b128 v[12:15], v3 offset:34848
	ds_read_b128 v[46:49], v3 offset:34864
	s_waitcnt vmcnt(17) lgkmcnt(3)
	v_fma_f32 v3, v43, v4, v38
	s_waitcnt vmcnt(16)
	v_fmac_f32_e32 v3, v42, v5
	s_waitcnt vmcnt(15)
	v_fmac_f32_e32 v3, v41, v6
	s_waitcnt vmcnt(14)
	v_fmac_f32_e32 v3, v40, v7
	s_waitcnt vmcnt(9) lgkmcnt(2)
	v_fmac_f32_e32 v3, v44, v8
	v_fmac_f32_e32 v3, v39, v9
	v_pk_mul_f32 v[4:5], v[32:33], v[10:11]
	s_waitcnt vmcnt(1)
	v_mul_f32_e32 v0, 0x3e000000, v0
	v_add_f32_e32 v3, v3, v4
	v_add_f32_e32 v3, v3, v5
	s_waitcnt lgkmcnt(1)
	v_pk_mul_f32 v[4:5], v[30:31], v[12:13]
	s_nop 0
	v_add_f32_e32 v3, v3, v4
	v_add_f32_e32 v3, v3, v5
	v_pk_mul_f32 v[4:5], v[28:29], v[14:15]
	s_nop 0
	v_add_f32_e32 v3, v3, v4
	v_add_f32_e32 v3, v3, v5
	s_waitcnt lgkmcnt(0)
	v_pk_mul_f32 v[4:5], v[24:25], v[46:47]
	s_nop 0
	v_add_f32_e32 v3, v3, v4
	v_add_f32_e32 v3, v3, v5
	v_pk_mul_f32 v[4:5], v[26:27], v[48:49]
	s_nop 0
	v_add_f32_e32 v3, v3, v4
	v_add_f32_e32 v3, v3, v5
	v_max_f32_e64 v19, -v3, 0
	v_mul_f32_e64 v3, |v3|, s5
	v_exp_f32_e32 v3, v3
	s_mov_b32 s5, 0x3f2aaaab
	v_add_f32_e32 v6, 1.0, v3
	v_add_f32_e32 v4, -1.0, v6
	v_sub_f32_e32 v5, v4, v6
	v_add_f32_e32 v5, 1.0, v5
	v_sub_f32_e32 v4, v3, v4
	v_add_f32_e32 v7, v4, v5
	v_frexp_mant_f32_e32 v4, v6
	v_cmp_gt_f32_e32 vcc, s5, v4
	v_cvt_f64_f32_e32 v[4:5], v6
	v_frexp_exp_i32_f64_e32 v4, v[4:5]
	v_subbrev_co_u32_e32 v12, vcc, 0, v4, vcc
	v_sub_u32_e32 v4, 0, v12
	v_ldexp_f32 v5, v6, v4
	v_add_f32_e32 v6, -1.0, v5
	v_add_f32_e32 v8, 1.0, v5
	v_ldexp_f32 v4, v7, v4
	v_add_f32_e32 v7, 1.0, v6
	v_add_f32_e32 v9, -1.0, v8
	v_sub_f32_e32 v7, v5, v7
	v_sub_f32_e32 v5, v5, v9
	v_add_f32_e32 v7, v4, v7
	v_add_f32_e32 v4, v4, v5
	v_add_f32_e32 v13, v8, v4
	v_rcp_f32_e32 v15, v13
	v_sub_f32_e32 v5, v13, v8
	v_sub_f32_e32 v14, v4, v5
	v_add_f32_e32 v5, v6, v7
	v_mul_f32_e32 v17, v5, v15
	v_sub_f32_e32 v4, v5, v6
	v_mul_f32_e32 v6, v13, v17
	v_fma_f32 v8, v17, v13, -v6
	v_fmac_f32_e32 v8, v17, v14
	v_sub_f32_e32 v16, v7, v4
	v_add_f32_e32 v4, v6, v8
	v_sub_f32_e32 v7, v5, v4
	v_pk_add_f32 v[10:11], v[4:5], v[6:7] neg_lo:[0,1] neg_hi:[0,1]
	v_mov_b32_e32 v9, v4
	v_pk_add_f32 v[4:5], v[10:11], v[8:9] neg_lo:[0,1] neg_hi:[0,1]
	s_mov_b32 s5, 0x7f800000
	v_add_f32_e32 v5, v16, v5
	v_add_f32_e32 v4, v4, v5
	v_add_f32_e32 v5, v7, v4
	v_mul_f32_e32 v16, v15, v5
	v_mul_f32_e32 v6, v13, v16
	v_fma_f32 v8, v16, v13, -v6
	v_fmac_f32_e32 v8, v16, v14
	v_sub_f32_e32 v7, v7, v5
	v_add_f32_e32 v13, v4, v7
	v_add_f32_e32 v4, v6, v8
	v_sub_f32_e32 v7, v5, v4
	v_pk_add_f32 v[10:11], v[4:5], v[6:7] neg_lo:[0,1] neg_hi:[0,1]
	v_mov_b32_e32 v9, v4
	v_pk_add_f32 v[4:5], v[10:11], v[8:9] neg_lo:[0,1] neg_hi:[0,1]
	v_cmp_neq_f32_e32 vcc, s5, v3
	v_add_f32_e32 v5, v13, v5
	v_add_f32_e32 v4, v4, v5
	v_add_f32_e32 v5, v17, v16
	v_add_f32_e32 v4, v7, v4
	v_sub_f32_e32 v6, v5, v17
	v_mul_f32_e32 v4, v15, v4
	v_sub_f32_e32 v6, v16, v6
	v_add_f32_e32 v6, v6, v4
	v_add_f32_e32 v8, v5, v6
	v_mul_f32_e32 v9, v8, v8
	v_fmamk_f32 v4, v9, 0x3e9b6dac, v236
	v_fmaak_f32 v199, v9, v4, 0x3f2aaada
	v_cvt_f32_i32_e32 v4, v12
	v_sub_f32_e32 v5, v8, v5
	v_sub_f32_e32 v5, v6, v5
	v_ldexp_f32 v10, v5, 1
	v_mul_f32_e32 v5, v8, v9
	v_ldexp_f32 v7, v8, 1
	v_pk_mul_f32 v[8:9], v[4:5], v[198:199]
	s_mov_b32 s5, 0x33800000
	v_fma_f32 v6, v4, s6, -v8
	v_fmac_f32_e32 v6, 0xb102e308, v4
	v_pk_add_f32 v[4:5], v[8:9], v[6:7]
	s_nop 0
	v_sub_f32_e32 v7, v5, v7
	v_sub_f32_e32 v7, v9, v7
	v_add_f32_e32 v11, v10, v7
	v_mov_b32_e32 v10, v8
	v_pk_add_f32 v[8:9], v[4:5], v[8:9] neg_lo:[0,1] neg_hi:[0,1]
	v_pk_add_f32 v[12:13], v[4:5], v[10:11]
	v_mov_b32_e32 v7, v4
	v_mov_b32_e32 v9, v13
; DI float sigm(float x) { return __builtin_amdgcn_rcpf(1.f + __expf(-x)); }
; DI float softplus_(float x) { return fmaxf(x, 0.f) + log1pf(__expf(-fabsf(x))); }
; template <int K, bool HG>
; DI void prep_gla(LAS unsigned char* lds, const Params& P, int l, int unit) {
;     ...
;     for (int i = 0; i < NE; ++i) { const int t = t0 + TS * i; qv[i] = 0.f; kv[i] = 0.f; float lg = 0.f;
;         if (t < up.nvalid) { const size_t row = (size_t)(up.row0 + t);
;             if (HG) { const int ch = up.h * 128 + k; const float fp = P32[row * LDP + C_BF + ch]; qv[i] = P32[row * LDP + C_BQ + ch];
;                 const float f = lb + (1.f - lb) * sigm(fp); lg = __logf(fmaxf(f, 1e-30f)); kv[i] = (1.f - lb) * sigm(-fp); }
;             else { const int ch = up.h * 64 + k; qv[i] = P32[row * LDP + C_CQ + ch] * 0.125f; kv[i] = P32[row * LDP + C_CK + ch]; float x = bias;
; #pragma unroll
;                 for (int rr = 0; rr < 16; ++rr) x += cl[t * 16 + rr] * wcol[rr];
;                 lg = -softplus_(-x) * (1.f / 16.f); } }
;         if (t < TR) Gs[t * K + k] = lg; }
	v_pk_add_f32 v[14:15], v[6:7], v[8:9] neg_lo:[0,1] neg_hi:[0,1]
	v_pk_add_f32 v[6:7], v[6:7], v[8:9]
	v_mov_b32_e32 v10, v11
	v_pk_add_f32 v[8:9], v[6:7], v[4:5] op_sel:[1,0] op_sel_hi:[0,1] neg_lo:[0,1] neg_hi:[0,1]
	v_pk_add_f32 v[16:17], v[12:13], v[8:9] op_sel_hi:[1,0] neg_lo:[0,1] neg_hi:[0,1]
	v_mov_b32_e32 v12, v13
	v_mov_b32_e32 v13, v7
	v_pk_mov_b32 v[8:9], v[4:5], v[8:9] op_sel:[1,0]
	v_mov_b32_e32 v11, v4
	v_pk_add_f32 v[8:9], v[12:13], v[8:9] neg_lo:[0,1] neg_hi:[0,1]
	v_mov_b32_e32 v16, v14
	v_pk_add_f32 v[4:5], v[10:11], v[8:9] neg_lo:[0,1] neg_hi:[0,1]
	v_mov_b32_e32 v15, v7
	v_pk_add_f32 v[8:9], v[16:17], v[4:5]
	s_nop 0
	v_pk_add_f32 v[10:11], v[8:9], v[8:9] op_sel:[0,1] op_sel_hi:[1,0]
	s_nop 0
	v_pk_add_f32 v[6:7], v[6:7], v[10:11] op_sel:[1,0] op_sel_hi:[0,1]
	v_mov_b32_e32 v9, v6
	v_pk_add_f32 v[12:13], v[8:9], v[14:15] neg_lo:[0,1] neg_hi:[0,1]
	v_mov_b32_e32 v5, v10
	v_sub_f32_e32 v7, v8, v12
	v_pk_add_f32 v[4:5], v[4:5], v[12:13] neg_lo:[0,1] neg_hi:[0,1]
	v_sub_f32_e32 v7, v14, v7
	v_add_f32_e32 v4, v4, v7
	v_add_f32_e32 v4, v4, v5
	v_add_f32_e32 v4, v6, v4
	v_cndmask_b32_e32 v4, v239, v4, vcc
	v_cmp_ngt_f32_e32 vcc, -1.0, v3
	s_nop 1
	v_cndmask_b32_e32 v4, v237, v4, vcc
	v_cmp_neq_f32_e32 vcc, -1.0, v3
	s_nop 1
	v_cndmask_b32_e32 v4, v203, v4, vcc
	v_cmp_lt_f32_e64 vcc, |v3|, s5
	s_nop 1
	v_cndmask_b32_e32 v3, v4, v3, vcc
	v_add_f32_e32 v3, v19, v3
	v_mul_f32_e32 v3, 0xbd800000, v3
.LBB0_596:
	s_or_b64 exec, exec, s[46:47]
	v_lshl_add_u32 v19, v20, 2, 0
	s_and_saveexec_b64 s[46:47], s[44:45]
	v_lshl_add_u32 v4, v21, 8, v19
	ds_write_b32 v4, v3
	s_or_b64 exec, exec, s[46:47]
	v_mov_b32_e32 v3, v1
	s_movk_i32 s5, 0xe00
	s_waitcnt vmcnt(0)
	v_mov_b64_e32 v[10:11], v[6:7]
	v_add_u32_e32 v36, 8, v21
	v_cmp_gt_i32_e64 s[46:47], s5, v18
	v_mov_b32_e32 v12, 0
	v_mov_b64_e32 v[8:9], v[4:5]
	v_mov_b64_e32 v[6:7], v[2:3]
	v_mov_b64_e32 v[4:5], v[0:1]
	s_and_saveexec_b64 s[48:49], s[46:47]
	s_cbranch_execz .LBB0_600
	v_add_u32_e32 v3, s3, v36
	v_mov_b64_e32 v[4:5], s[64:65]
	v_mad_i64_i32 v[4:5], s[6:7], v3, s76, v[4:5]
	v_lshl_add_u64 v[4:5], v[22:23], 2, v[4:5]
	v_add_co_u32_e32 v4, vcc, 0x3000, v4
	v_lshl_add_u32 v17, v36, 6, 0
	s_nop 0
	v_addc_co_u32_e32 v5, vcc, 0, v5, vcc
	v_mov_b32_e32 v3, v76
	s_mov_b32 s5, 0xbfb8aa3b
	s_mov_b32 s6, 0x3f317218
	s_waitcnt vmcnt(0)
	v_mul_f32_e32 v16, 0x3e000000, v3
	v_mov_b32_e32 v3, v77
	ds_read_b128 v[4:7], v17 offset:34816
	ds_read_b128 v[8:11], v17 offset:34832
	ds_read_b128 v[12:15], v17 offset:34848
	ds_read_b128 v[46:49], v17 offset:34864
	s_waitcnt lgkmcnt(3)
	v_fma_f32 v17, v43, v4, v38
	v_fmac_f32_e32 v17, v42, v5
	v_fmac_f32_e32 v17, v41, v6
	v_fmac_f32_e32 v17, v40, v7
	s_waitcnt lgkmcnt(2)
	v_fmac_f32_e32 v17, v44, v8
	v_fmac_f32_e32 v17, v39, v9
	v_pk_mul_f32 v[4:5], v[32:33], v[10:11]
	s_nop 0
	v_add_f32_e32 v4, v17, v4
	v_add_f32_e32 v6, v4, v5
	s_waitcnt lgkmcnt(1)
	v_pk_mul_f32 v[4:5], v[30:31], v[12:13]
	s_nop 0
	v_add_f32_e32 v4, v6, v4
	v_add_f32_e32 v6, v4, v5
	v_pk_mul_f32 v[4:5], v[28:29], v[14:15]
	s_nop 0
	v_add_f32_e32 v4, v6, v4
	v_add_f32_e32 v6, v4, v5
	s_waitcnt lgkmcnt(0)
	v_pk_mul_f32 v[4:5], v[24:25], v[46:47]
	s_nop 0
	v_add_f32_e32 v4, v6, v4
	v_add_f32_e32 v6, v4, v5
	v_pk_mul_f32 v[4:5], v[26:27], v[48:49]
	s_nop 0
	v_add_f32_e32 v4, v6, v4
	v_add_f32_e32 v12, v4, v5
	s_waitcnt vmcnt(0)
	v_mov_b64_e32 v[10:11], v[6:7]
	v_mov_b64_e32 v[8:9], v[4:5]
	v_mov_b64_e32 v[6:7], v[2:3]
	v_mov_b64_e32 v[4:5], v[0:1]
	v_mul_f32_e64 v6, |v12|, s5
	v_exp_f32_e32 v37, v6
	s_mov_b32 s5, 0x3f2aaaab
	v_mov_b32_e32 v5, v16
	v_max_f32_e64 v0, -v12, 0
	v_add_f32_e32 v8, 1.0, v37
	v_add_f32_e32 v6, -1.0, v8
	v_sub_f32_e32 v7, v6, v8
	v_add_f32_e32 v7, 1.0, v7
	v_sub_f32_e32 v6, v37, v6
	v_add_f32_e32 v9, v6, v7
	v_frexp_mant_f32_e32 v6, v8
	v_cmp_gt_f32_e32 vcc, s5, v6
	v_cvt_f64_f32_e32 v[6:7], v8
	v_frexp_exp_i32_f64_e32 v6, v[6:7]
	v_subbrev_co_u32_e32 v14, vcc, 0, v6, vcc
	v_sub_u32_e32 v6, 0, v14
	v_ldexp_f32 v7, v8, v6
	v_add_f32_e32 v8, -1.0, v7
	v_add_f32_e32 v10, 1.0, v7
	v_ldexp_f32 v6, v9, v6
	v_add_f32_e32 v9, 1.0, v8
	v_add_f32_e32 v11, -1.0, v10
	v_sub_f32_e32 v9, v7, v9
	v_sub_f32_e32 v7, v7, v11
	v_add_f32_e32 v9, v6, v9
	v_add_f32_e32 v6, v6, v7
	v_add_f32_e32 v15, v10, v6
	v_rcp_f32_e32 v17, v15
	v_sub_f32_e32 v7, v15, v10
	v_sub_f32_e32 v16, v6, v7
	v_add_f32_e32 v7, v8, v9
	v_mul_f32_e32 v46, v7, v17
	v_sub_f32_e32 v6, v7, v8
	v_mul_f32_e32 v8, v15, v46
	v_fma_f32 v10, v46, v15, -v8
	v_fmac_f32_e32 v10, v46, v16
	v_sub_f32_e32 v45, v9, v6
	v_add_f32_e32 v6, v8, v10
	v_sub_f32_e32 v9, v7, v6
	v_pk_add_f32 v[12:13], v[6:7], v[8:9] neg_lo:[0,1] neg_hi:[0,1]
	v_mov_b32_e32 v11, v6
	v_pk_add_f32 v[6:7], v[12:13], v[10:11] neg_lo:[0,1] neg_hi:[0,1]
	s_mov_b32 s5, 0x7f800000
	v_add_f32_e32 v7, v45, v7
	v_add_f32_e32 v6, v6, v7
	v_add_f32_e32 v7, v9, v6
	v_mul_f32_e32 v45, v17, v7
	v_mul_f32_e32 v8, v15, v45
	v_fma_f32 v10, v45, v15, -v8
	v_fmac_f32_e32 v10, v45, v16
	v_sub_f32_e32 v9, v9, v7
	v_add_f32_e32 v15, v6, v9
	v_add_f32_e32 v6, v8, v10
	v_sub_f32_e32 v9, v7, v6
	v_pk_add_f32 v[12:13], v[6:7], v[8:9] neg_lo:[0,1] neg_hi:[0,1]
	v_mov_b32_e32 v11, v6
	v_pk_add_f32 v[6:7], v[12:13], v[10:11] neg_lo:[0,1] neg_hi:[0,1]
	v_cmp_neq_f32_e32 vcc, s5, v37
	v_add_f32_e32 v7, v15, v7
	v_add_f32_e32 v6, v6, v7
	v_add_f32_e32 v7, v46, v45
	v_add_f32_e32 v6, v9, v6
	v_sub_f32_e32 v8, v7, v46
	v_mul_f32_e32 v6, v17, v6
	v_sub_f32_e32 v8, v45, v8
	v_add_f32_e32 v8, v8, v6
	v_add_f32_e32 v10, v7, v8
	v_mul_f32_e32 v11, v10, v10
	v_fmamk_f32 v6, v11, 0x3e9b6dac, v236
	v_fmaak_f32 v199, v11, v6, 0x3f2aaada
	v_cvt_f32_i32_e32 v6, v14
	v_sub_f32_e32 v7, v10, v7
; DI float sigm(float x) { return __builtin_amdgcn_rcpf(1.f + __expf(-x)); }
; DI float softplus_(float x) { return fmaxf(x, 0.f) + log1pf(__expf(-fabsf(x))); }
; template <int K, bool HG>
; DI void prep_gla(LAS unsigned char* lds, const Params& P, int l, int unit) {
;     ...
;     for (int i = 0; i < NE; ++i) { const int t = t0 + TS * i; qv[i] = 0.f; kv[i] = 0.f; float lg = 0.f;
;         if (t < up.nvalid) { const size_t row = (size_t)(up.row0 + t);
;             if (HG) { const int ch = up.h * 128 + k; const float fp = P32[row * LDP + C_BF + ch]; qv[i] = P32[row * LDP + C_BQ + ch];
;                 const float f = lb + (1.f - lb) * sigm(fp); lg = __logf(fmaxf(f, 1e-30f)); kv[i] = (1.f - lb) * sigm(-fp); }
;             else { const int ch = up.h * 64 + k; qv[i] = P32[row * LDP + C_CQ + ch] * 0.125f; kv[i] = P32[row * LDP + C_CK + ch]; float x = bias;
; #pragma unroll
;                 for (int rr = 0; rr < 16; ++rr) x += cl[t * 16 + rr] * wcol[rr];
;                 lg = -softplus_(-x) * (1.f / 16.f); } }
;         if (t < TR) Gs[t * K + k] = lg; }
	v_sub_f32_e32 v7, v8, v7
	v_ldexp_f32 v12, v7, 1
	v_mul_f32_e32 v7, v10, v11
	v_ldexp_f32 v9, v10, 1
	v_pk_mul_f32 v[10:11], v[6:7], v[198:199]
	s_mov_b32 s5, 0x33800000
	v_fma_f32 v8, v6, s6, -v10
	v_fmac_f32_e32 v8, 0xb102e308, v6
	v_pk_add_f32 v[6:7], v[10:11], v[8:9]
	s_nop 0
	v_sub_f32_e32 v9, v7, v9
	v_sub_f32_e32 v9, v11, v9
	v_add_f32_e32 v13, v12, v9
	v_mov_b32_e32 v12, v10
	v_pk_add_f32 v[10:11], v[6:7], v[10:11] neg_lo:[0,1] neg_hi:[0,1]
	v_pk_add_f32 v[14:15], v[6:7], v[12:13]
	v_mov_b32_e32 v9, v6
	v_mov_b32_e32 v11, v15
	v_pk_add_f32 v[16:17], v[8:9], v[10:11] neg_lo:[0,1] neg_hi:[0,1]
	v_pk_add_f32 v[8:9], v[8:9], v[10:11]
	v_mov_b32_e32 v12, v13
	v_pk_add_f32 v[10:11], v[8:9], v[6:7] op_sel:[1,0] op_sel_hi:[0,1] neg_lo:[0,1] neg_hi:[0,1]
	v_pk_add_f32 v[46:47], v[14:15], v[10:11] op_sel_hi:[1,0] neg_lo:[0,1] neg_hi:[0,1]
	v_mov_b32_e32 v14, v15
	v_mov_b32_e32 v15, v9
	v_pk_mov_b32 v[10:11], v[6:7], v[10:11] op_sel:[1,0]
	v_mov_b32_e32 v13, v6
	v_pk_add_f32 v[10:11], v[14:15], v[10:11] neg_lo:[0,1] neg_hi:[0,1]
	v_mov_b32_e32 v46, v16
	v_pk_add_f32 v[6:7], v[12:13], v[10:11] neg_lo:[0,1] neg_hi:[0,1]
	v_mov_b32_e32 v17, v9
	v_pk_add_f32 v[10:11], v[46:47], v[6:7]
	s_nop 0
	v_pk_add_f32 v[12:13], v[10:11], v[10:11] op_sel:[0,1] op_sel_hi:[1,0]
	s_nop 0
	v_pk_add_f32 v[8:9], v[8:9], v[12:13] op_sel:[1,0] op_sel_hi:[0,1]
	v_mov_b32_e32 v11, v8
	v_pk_add_f32 v[14:15], v[10:11], v[16:17] neg_lo:[0,1] neg_hi:[0,1]
	v_mov_b32_e32 v7, v12
	v_sub_f32_e32 v9, v10, v14
	v_pk_add_f32 v[6:7], v[6:7], v[14:15] neg_lo:[0,1] neg_hi:[0,1]
	v_sub_f32_e32 v9, v16, v9
	v_add_f32_e32 v6, v6, v9
	v_add_f32_e32 v6, v6, v7
	v_add_f32_e32 v6, v8, v6
	v_cndmask_b32_e32 v6, v239, v6, vcc
	v_cmp_ngt_f32_e32 vcc, -1.0, v37
	s_nop 1
	v_cndmask_b32_e32 v6, v237, v6, vcc
	v_cmp_neq_f32_e32 vcc, -1.0, v37
	s_nop 1
	v_cndmask_b32_e32 v6, v203, v6, vcc
	v_cmp_lt_f32_e64 vcc, |v37|, s5
	s_nop 1
	v_cndmask_b32_e32 v6, v6, v37, vcc
	v_add_f32_e32 v0, v0, v6
	v_mul_f32_e32 v12, 0xbd800000, v0
.LBB0_600:
	s_or_b64 exec, exec, s[48:49]
	v_lshl_add_u32 v37, v36, 8, v19
	s_and_saveexec_b64 s[48:49], s[46:47]
	ds_write_b32 v37, v12
	s_or_b64 exec, exec, s[48:49]
	s_movk_i32 s5, 0xc00
	v_add_u32_e32 v0, 16, v21
	v_mov_b32_e32 v8, s29
	v_mov_b32_e32 v6, s29
	v_cmp_gt_i32_e64 s[48:49], s5, v18
	v_mov_b32_e32 v7, 0
	s_and_saveexec_b64 s[50:51], s[48:49]
	s_cbranch_execz .LBB0_604
	v_add_u32_e32 v8, s3, v0
	v_mov_b64_e32 v[6:7], s[64:65]
	v_mad_i64_i32 v[6:7], s[6:7], v8, s76, v[6:7]
	v_lshl_add_u64 v[6:7], v[22:23], 2, v[6:7]
	v_add_co_u32_e32 v6, vcc, 0x3000, v6
	s_mov_b32 s5, 0xbfb8aa3b
	s_nop 0
	v_addc_co_u32_e32 v7, vcc, 0, v7, vcc
	v_mov_b32_e32 v8, v78
	s_mov_b32 s6, 0x3f317218
	v_mov_b32_e32 v6, v79
	v_lshl_add_u32 v7, v0, 6, 0
	ds_read_b128 v[10:13], v7 offset:34816
	ds_read_b128 v[14:17], v7 offset:34832
	ds_read_b128 v[46:49], v7 offset:34848
	ds_read_b128 v[50:53], v7 offset:34864
	s_waitcnt lgkmcnt(3)
	v_fma_f32 v7, v43, v10, v38
	v_fmac_f32_e32 v7, v42, v11
	v_fmac_f32_e32 v7, v41, v12
	v_fmac_f32_e32 v7, v40, v13
	s_waitcnt lgkmcnt(2)
	v_fmac_f32_e32 v7, v44, v14
	v_fmac_f32_e32 v7, v39, v15
	v_pk_mul_f32 v[10:11], v[32:33], v[16:17]
	s_waitcnt vmcnt(1)
	v_mul_f32_e32 v8, 0x3e000000, v8
	v_add_f32_e32 v7, v7, v10
	v_add_f32_e32 v7, v7, v11
	s_waitcnt lgkmcnt(1)
	v_pk_mul_f32 v[10:11], v[30:31], v[46:47]
	s_nop 0
	v_add_f32_e32 v7, v7, v10
	v_add_f32_e32 v7, v7, v11
	v_pk_mul_f32 v[10:11], v[28:29], v[48:49]
	s_nop 0
	v_add_f32_e32 v7, v7, v10
	v_add_f32_e32 v7, v7, v11
	s_waitcnt lgkmcnt(0)
	v_pk_mul_f32 v[10:11], v[24:25], v[50:51]
	s_nop 0
	v_add_f32_e32 v7, v7, v10
	v_add_f32_e32 v7, v7, v11
	v_pk_mul_f32 v[10:11], v[26:27], v[52:53]
	s_nop 0
	v_add_f32_e32 v7, v7, v10
	v_add_f32_e32 v7, v7, v11
	v_max_f32_e64 v9, -v7, 0
	v_mul_f32_e64 v7, |v7|, s5
	v_exp_f32_e32 v7, v7
	s_mov_b32 s5, 0x3f2aaaab
	v_add_f32_e32 v12, 1.0, v7
	v_add_f32_e32 v10, -1.0, v12
	v_sub_f32_e32 v11, v10, v12
	v_add_f32_e32 v11, 1.0, v11
	v_sub_f32_e32 v10, v7, v10
	v_add_f32_e32 v13, v10, v11
	v_frexp_mant_f32_e32 v10, v12
	v_cmp_gt_f32_e32 vcc, s5, v10
	v_cvt_f64_f32_e32 v[10:11], v12
	v_frexp_exp_i32_f64_e32 v10, v[10:11]
	v_subbrev_co_u32_e32 v45, vcc, 0, v10, vcc
	v_sub_u32_e32 v10, 0, v45
	v_ldexp_f32 v11, v12, v10
	v_add_f32_e32 v12, -1.0, v11
	v_add_f32_e32 v14, 1.0, v11
	v_ldexp_f32 v10, v13, v10
	v_add_f32_e32 v13, 1.0, v12
	v_add_f32_e32 v15, -1.0, v14
	v_sub_f32_e32 v13, v11, v13
	v_sub_f32_e32 v11, v11, v15
	v_add_f32_e32 v13, v10, v13
	v_add_f32_e32 v10, v10, v11
	v_add_f32_e32 v46, v14, v10
	v_rcp_f32_e32 v48, v46
	v_sub_f32_e32 v11, v46, v14
	v_sub_f32_e32 v47, v10, v11
	v_add_f32_e32 v11, v12, v13
	v_mul_f32_e32 v50, v11, v48
	v_sub_f32_e32 v10, v11, v12
	v_mul_f32_e32 v12, v46, v50
	v_fma_f32 v14, v50, v46, -v12
	v_fmac_f32_e32 v14, v50, v47
	v_sub_f32_e32 v49, v13, v10
	v_add_f32_e32 v10, v12, v14
	v_sub_f32_e32 v13, v11, v10
	v_pk_add_f32 v[16:17], v[10:11], v[12:13] neg_lo:[0,1] neg_hi:[0,1]
	v_mov_b32_e32 v15, v10
	v_pk_add_f32 v[10:11], v[16:17], v[14:15] neg_lo:[0,1] neg_hi:[0,1]
	s_mov_b32 s5, 0x7f800000
	v_add_f32_e32 v11, v49, v11
	v_add_f32_e32 v10, v10, v11
	v_add_f32_e32 v11, v13, v10
	v_mul_f32_e32 v49, v48, v11
	v_mul_f32_e32 v12, v46, v49
	v_fma_f32 v14, v49, v46, -v12
	v_fmac_f32_e32 v14, v49, v47
	v_sub_f32_e32 v13, v13, v11
	v_add_f32_e32 v46, v10, v13
	v_add_f32_e32 v10, v12, v14
	v_sub_f32_e32 v13, v11, v10
	v_pk_add_f32 v[16:17], v[10:11], v[12:13] neg_lo:[0,1] neg_hi:[0,1]
	v_mov_b32_e32 v15, v10
	v_pk_add_f32 v[10:11], v[16:17], v[14:15] neg_lo:[0,1] neg_hi:[0,1]
	v_cmp_neq_f32_e32 vcc, s5, v7
	v_add_f32_e32 v11, v46, v11
	v_add_f32_e32 v10, v10, v11
; DI float sigm(float x) { return __builtin_amdgcn_rcpf(1.f + __expf(-x)); }
; DI float softplus_(float x) { return fmaxf(x, 0.f) + log1pf(__expf(-fabsf(x))); }
; template <int K, bool HG>
; DI void prep_gla(LAS unsigned char* lds, const Params& P, int l, int unit) {
;     ...
;     for (int i = 0; i < NE; ++i) { const int t = t0 + TS * i; qv[i] = 0.f; kv[i] = 0.f; float lg = 0.f;
;         if (t < up.nvalid) { const size_t row = (size_t)(up.row0 + t);
;             if (HG) { const int ch = up.h * 128 + k; const float fp = P32[row * LDP + C_BF + ch]; qv[i] = P32[row * LDP + C_BQ + ch];
;                 const float f = lb + (1.f - lb) * sigm(fp); lg = __logf(fmaxf(f, 1e-30f)); kv[i] = (1.f - lb) * sigm(-fp); }
;             else { const int ch = up.h * 64 + k; qv[i] = P32[row * LDP + C_CQ + ch] * 0.125f; kv[i] = P32[row * LDP + C_CK + ch]; float x = bias;
; #pragma unroll
;                 for (int rr = 0; rr < 16; ++rr) x += cl[t * 16 + rr] * wcol[rr];
;                 lg = -softplus_(-x) * (1.f / 16.f); } }
;         if (t < TR) Gs[t * K + k] = lg; }
	v_add_f32_e32 v11, v50, v49
	v_add_f32_e32 v10, v13, v10
	v_sub_f32_e32 v12, v11, v50
	v_mul_f32_e32 v10, v48, v10
	v_sub_f32_e32 v12, v49, v12
	v_add_f32_e32 v12, v12, v10
	v_add_f32_e32 v14, v11, v12
	v_mul_f32_e32 v15, v14, v14
	v_fmamk_f32 v10, v15, 0x3e9b6dac, v236
	v_fmaak_f32 v199, v15, v10, 0x3f2aaada
	v_cvt_f32_i32_e32 v10, v45
	v_sub_f32_e32 v11, v14, v11
	v_sub_f32_e32 v11, v12, v11
	v_ldexp_f32 v16, v11, 1
	v_mul_f32_e32 v11, v14, v15
	v_ldexp_f32 v13, v14, 1
	v_pk_mul_f32 v[14:15], v[10:11], v[198:199]
	s_mov_b32 s5, 0x33800000
	v_fma_f32 v12, v10, s6, -v14
	v_fmac_f32_e32 v12, 0xb102e308, v10
	v_pk_add_f32 v[10:11], v[14:15], v[12:13]
	s_nop 0
	v_sub_f32_e32 v13, v11, v13
	v_sub_f32_e32 v13, v15, v13
	v_add_f32_e32 v17, v16, v13
	v_mov_b32_e32 v16, v14
	v_pk_add_f32 v[14:15], v[10:11], v[14:15] neg_lo:[0,1] neg_hi:[0,1]
	v_pk_add_f32 v[46:47], v[10:11], v[16:17]
	v_mov_b32_e32 v13, v10
	v_mov_b32_e32 v15, v47
	v_pk_add_f32 v[48:49], v[12:13], v[14:15] neg_lo:[0,1] neg_hi:[0,1]
	v_pk_add_f32 v[12:13], v[12:13], v[14:15]
	v_mov_b32_e32 v16, v17
	v_pk_add_f32 v[14:15], v[12:13], v[10:11] op_sel:[1,0] op_sel_hi:[0,1] neg_lo:[0,1] neg_hi:[0,1]
	v_pk_add_f32 v[50:51], v[46:47], v[14:15] op_sel_hi:[1,0] neg_lo:[0,1] neg_hi:[0,1]
	v_mov_b32_e32 v46, v47
	v_mov_b32_e32 v47, v13
	v_pk_mov_b32 v[14:15], v[10:11], v[14:15] op_sel:[1,0]
	v_mov_b32_e32 v17, v10
	v_pk_add_f32 v[14:15], v[46:47], v[14:15] neg_lo:[0,1] neg_hi:[0,1]
	v_mov_b32_e32 v50, v48
	v_pk_add_f32 v[10:11], v[16:17], v[14:15] neg_lo:[0,1] neg_hi:[0,1]
	v_mov_b32_e32 v49, v13
	v_pk_add_f32 v[14:15], v[50:51], v[10:11]
	s_nop 0
	v_pk_add_f32 v[16:17], v[14:15], v[14:15] op_sel:[0,1] op_sel_hi:[1,0]
	s_nop 0
	v_pk_add_f32 v[12:13], v[12:13], v[16:17] op_sel:[1,0] op_sel_hi:[0,1]
	v_mov_b32_e32 v15, v12
	v_pk_add_f32 v[46:47], v[14:15], v[48:49] neg_lo:[0,1] neg_hi:[0,1]
	v_mov_b32_e32 v11, v16
	v_sub_f32_e32 v13, v14, v46
	v_pk_add_f32 v[10:11], v[10:11], v[46:47] neg_lo:[0,1] neg_hi:[0,1]
	v_sub_f32_e32 v13, v48, v13
	v_add_f32_e32 v10, v10, v13
	v_add_f32_e32 v10, v10, v11
	v_add_f32_e32 v10, v12, v10
	v_cndmask_b32_e32 v10, v239, v10, vcc
	v_cmp_ngt_f32_e32 vcc, -1.0, v7
	s_nop 1
	v_cndmask_b32_e32 v10, v237, v10, vcc
	v_cmp_neq_f32_e32 vcc, -1.0, v7
	s_nop 1
	v_cndmask_b32_e32 v10, v203, v10, vcc
	v_cmp_lt_f32_e64 vcc, |v7|, s5
	s_nop 1
	v_cndmask_b32_e32 v7, v10, v7, vcc
	v_add_f32_e32 v7, v9, v7
	v_mul_f32_e32 v7, 0xbd800000, v7
.LBB0_604:
	s_or_b64 exec, exec, s[50:51]
	v_lshl_add_u32 v46, v0, 8, v19
	s_and_saveexec_b64 s[50:51], s[48:49]
	ds_write_b32 v46, v7
	s_or_b64 exec, exec, s[50:51]
	s_movk_i32 s5, 0xa00
	v_add_u32_e32 v45, 24, v21
	v_mov_b32_e32 v9, s29
	v_mov_b32_e32 v7, s29
	v_cmp_gt_i32_e64 s[50:51], s5, v18
	v_mov_b32_e32 v10, 0
	s_and_saveexec_b64 s[52:53], s[50:51]
	s_cbranch_execz .LBB0_608
	v_add_u32_e32 v7, s3, v45
	v_mov_b64_e32 v[10:11], s[64:65]
	v_mad_i64_i32 v[10:11], s[6:7], v7, s76, v[10:11]
	v_lshl_add_u64 v[10:11], v[22:23], 2, v[10:11]
	v_add_co_u32_e32 v10, vcc, 0x3000, v10
	v_lshl_add_u32 v47, v45, 6, 0
	s_nop 0
	v_addc_co_u32_e32 v11, vcc, 0, v11, vcc
	v_mov_b32_e32 v7, v80
	s_mov_b32 s5, 0xbfb8aa3b
	s_mov_b32 s6, 0x3f317218
	s_waitcnt vmcnt(0)
	v_mul_f32_e32 v9, 0x3e000000, v7
	v_mov_b32_e32 v7, v81
	ds_read_b128 v[10:13], v47 offset:34816
	ds_read_b128 v[14:17], v47 offset:34832
	ds_read_b128 v[48:51], v47 offset:34848
	ds_read_b128 v[52:55], v47 offset:34864
	s_waitcnt lgkmcnt(3)
	v_fma_f32 v47, v43, v10, v38
	v_fmac_f32_e32 v47, v42, v11
	v_fmac_f32_e32 v47, v41, v12
	v_fmac_f32_e32 v47, v40, v13
	s_waitcnt lgkmcnt(2)
	v_fmac_f32_e32 v47, v44, v14
	v_fmac_f32_e32 v47, v39, v15
	v_pk_mul_f32 v[10:11], v[32:33], v[16:17]
	s_nop 0
	v_add_f32_e32 v10, v47, v10
	v_add_f32_e32 v12, v10, v11
	s_waitcnt lgkmcnt(1)
	v_pk_mul_f32 v[10:11], v[30:31], v[48:49]
	s_nop 0
	v_add_f32_e32 v10, v12, v10
	v_add_f32_e32 v12, v10, v11
	v_pk_mul_f32 v[10:11], v[28:29], v[50:51]
	s_nop 0
	v_add_f32_e32 v10, v12, v10
	v_add_f32_e32 v12, v10, v11
	s_waitcnt lgkmcnt(0)
	v_pk_mul_f32 v[10:11], v[24:25], v[52:53]
	s_nop 0
	v_add_f32_e32 v10, v12, v10
	v_add_f32_e32 v12, v10, v11
	v_pk_mul_f32 v[10:11], v[26:27], v[54:55]
	s_nop 0
	v_add_f32_e32 v10, v12, v10
	v_add_f32_e32 v10, v10, v11
	v_max_f32_e64 v47, -v10, 0
	v_mul_f32_e64 v10, |v10|, s5
	v_exp_f32_e32 v54, v10
	s_mov_b32 s5, 0x3f2aaaab
	v_add_f32_e32 v12, 1.0, v54
	v_add_f32_e32 v10, -1.0, v12
	v_sub_f32_e32 v11, v10, v12
	v_add_f32_e32 v11, 1.0, v11
	v_sub_f32_e32 v10, v54, v10
	v_add_f32_e32 v13, v10, v11
	v_frexp_mant_f32_e32 v10, v12
	v_cmp_gt_f32_e32 vcc, s5, v10
	v_cvt_f64_f32_e32 v[10:11], v12
	v_frexp_exp_i32_f64_e32 v10, v[10:11]
	v_subbrev_co_u32_e32 v48, vcc, 0, v10, vcc
	v_sub_u32_e32 v10, 0, v48
	v_ldexp_f32 v11, v12, v10
	v_add_f32_e32 v12, -1.0, v11
	v_add_f32_e32 v14, 1.0, v11
	v_ldexp_f32 v10, v13, v10
	v_add_f32_e32 v13, 1.0, v12
	v_add_f32_e32 v15, -1.0, v14
	v_sub_f32_e32 v13, v11, v13
	v_sub_f32_e32 v11, v11, v15
	v_add_f32_e32 v13, v10, v13
	v_add_f32_e32 v10, v10, v11
	v_add_f32_e32 v49, v14, v10
	v_rcp_f32_e32 v51, v49
	v_sub_f32_e32 v11, v49, v14
	v_sub_f32_e32 v50, v10, v11
	v_add_f32_e32 v11, v12, v13
	v_mul_f32_e32 v53, v11, v51
	v_sub_f32_e32 v10, v11, v12
	v_mul_f32_e32 v12, v49, v53
	v_fma_f32 v14, v53, v49, -v12
	v_fmac_f32_e32 v14, v53, v50
	v_sub_f32_e32 v52, v13, v10
	v_add_f32_e32 v10, v12, v14
	v_sub_f32_e32 v13, v11, v10
	v_pk_add_f32 v[16:17], v[10:11], v[12:13] neg_lo:[0,1] neg_hi:[0,1]
	v_mov_b32_e32 v15, v10
	v_pk_add_f32 v[10:11], v[16:17], v[14:15] neg_lo:[0,1] neg_hi:[0,1]
	s_mov_b32 s5, 0x7f800000
	v_add_f32_e32 v11, v52, v11
	v_add_f32_e32 v10, v10, v11
; DI float sigm(float x) { return __builtin_amdgcn_rcpf(1.f + __expf(-x)); }
; DI float softplus_(float x) { return fmaxf(x, 0.f) + log1pf(__expf(-fabsf(x))); }
; template <int K, bool HG>
; DI void prep_gla(LAS unsigned char* lds, const Params& P, int l, int unit) {
;     ...
;     for (int i = 0; i < NE; ++i) { const int t = t0 + TS * i; qv[i] = 0.f; kv[i] = 0.f; float lg = 0.f;
;         if (t < up.nvalid) { const size_t row = (size_t)(up.row0 + t);
;             if (HG) { const int ch = up.h * 128 + k; const float fp = P32[row * LDP + C_BF + ch]; qv[i] = P32[row * LDP + C_BQ + ch];
;                 const float f = lb + (1.f - lb) * sigm(fp); lg = __logf(fmaxf(f, 1e-30f)); kv[i] = (1.f - lb) * sigm(-fp); }
;             else { const int ch = up.h * 64 + k; qv[i] = P32[row * LDP + C_CQ + ch] * 0.125f; kv[i] = P32[row * LDP + C_CK + ch]; float x = bias;
; #pragma unroll
;                 for (int rr = 0; rr < 16; ++rr) x += cl[t * 16 + rr] * wcol[rr];
;                 lg = -softplus_(-x) * (1.f / 16.f); } }
;         if (t < TR) Gs[t * K + k] = lg; }
	v_add_f32_e32 v11, v13, v10
	v_mul_f32_e32 v52, v51, v11
	v_mul_f32_e32 v12, v49, v52
	v_fma_f32 v14, v52, v49, -v12
	v_fmac_f32_e32 v14, v52, v50
	v_sub_f32_e32 v13, v13, v11
	v_add_f32_e32 v49, v10, v13
	v_add_f32_e32 v10, v12, v14
	v_sub_f32_e32 v13, v11, v10
	v_pk_add_f32 v[16:17], v[10:11], v[12:13] neg_lo:[0,1] neg_hi:[0,1]
	v_mov_b32_e32 v15, v10
	v_pk_add_f32 v[10:11], v[16:17], v[14:15] neg_lo:[0,1] neg_hi:[0,1]
	v_cmp_neq_f32_e32 vcc, s5, v54
	v_add_f32_e32 v11, v49, v11
	v_add_f32_e32 v10, v10, v11
	v_add_f32_e32 v11, v53, v52
	v_add_f32_e32 v10, v13, v10
	v_sub_f32_e32 v12, v11, v53
	v_mul_f32_e32 v10, v51, v10
	v_sub_f32_e32 v12, v52, v12
	v_add_f32_e32 v12, v12, v10
	v_add_f32_e32 v14, v11, v12
	v_mul_f32_e32 v15, v14, v14
	v_fmamk_f32 v10, v15, 0x3e9b6dac, v236
	v_fmaak_f32 v199, v15, v10, 0x3f2aaada
	v_cvt_f32_i32_e32 v10, v48
	v_sub_f32_e32 v11, v14, v11
	v_sub_f32_e32 v11, v12, v11
	v_ldexp_f32 v16, v11, 1
	v_mul_f32_e32 v11, v14, v15
	v_ldexp_f32 v13, v14, 1
	v_pk_mul_f32 v[14:15], v[10:11], v[198:199]
	s_mov_b32 s5, 0x33800000
	v_fma_f32 v12, v10, s6, -v14
	v_fmac_f32_e32 v12, 0xb102e308, v10
	v_pk_add_f32 v[10:11], v[14:15], v[12:13]
	s_nop 0
	v_sub_f32_e32 v13, v11, v13
	v_sub_f32_e32 v13, v15, v13
	v_add_f32_e32 v17, v16, v13
	v_mov_b32_e32 v16, v14
	v_pk_add_f32 v[14:15], v[10:11], v[14:15] neg_lo:[0,1] neg_hi:[0,1]
	v_pk_add_f32 v[48:49], v[10:11], v[16:17]
	v_mov_b32_e32 v13, v10
	v_mov_b32_e32 v15, v49
	v_pk_add_f32 v[50:51], v[12:13], v[14:15] neg_lo:[0,1] neg_hi:[0,1]
	v_pk_add_f32 v[12:13], v[12:13], v[14:15]
	v_mov_b32_e32 v16, v17
	v_pk_add_f32 v[14:15], v[12:13], v[10:11] op_sel:[1,0] op_sel_hi:[0,1] neg_lo:[0,1] neg_hi:[0,1]
	v_pk_add_f32 v[52:53], v[48:49], v[14:15] op_sel_hi:[1,0] neg_lo:[0,1] neg_hi:[0,1]
	v_mov_b32_e32 v48, v49
	v_mov_b32_e32 v49, v13
	v_pk_mov_b32 v[14:15], v[10:11], v[14:15] op_sel:[1,0]
	v_mov_b32_e32 v17, v10
	v_pk_add_f32 v[14:15], v[48:49], v[14:15] neg_lo:[0,1] neg_hi:[0,1]
	v_mov_b32_e32 v52, v50
	v_pk_add_f32 v[10:11], v[16:17], v[14:15] neg_lo:[0,1] neg_hi:[0,1]
	v_mov_b32_e32 v51, v13
	v_pk_add_f32 v[14:15], v[52:53], v[10:11]
	s_nop 0
	v_pk_add_f32 v[16:17], v[14:15], v[14:15] op_sel:[0,1] op_sel_hi:[1,0]
	s_nop 0
	v_pk_add_f32 v[12:13], v[12:13], v[16:17] op_sel:[1,0] op_sel_hi:[0,1]
	v_mov_b32_e32 v15, v12
	v_pk_add_f32 v[48:49], v[14:15], v[50:51] neg_lo:[0,1] neg_hi:[0,1]
	v_mov_b32_e32 v11, v16
	v_sub_f32_e32 v13, v14, v48
	v_pk_add_f32 v[10:11], v[10:11], v[48:49] neg_lo:[0,1] neg_hi:[0,1]
	v_sub_f32_e32 v13, v50, v13
	v_add_f32_e32 v10, v10, v13
	v_add_f32_e32 v10, v10, v11
	v_add_f32_e32 v10, v12, v10
	v_cndmask_b32_e32 v10, v239, v10, vcc
	v_cmp_ngt_f32_e32 vcc, -1.0, v54
	s_nop 1
	v_cndmask_b32_e32 v10, v237, v10, vcc
	v_cmp_neq_f32_e32 vcc, -1.0, v54
	s_nop 1
	v_cndmask_b32_e32 v10, v203, v10, vcc
	v_cmp_lt_f32_e64 vcc, |v54|, s5
	s_nop 1
	v_cndmask_b32_e32 v10, v10, v54, vcc
	v_add_f32_e32 v10, v47, v10
	v_mul_f32_e32 v10, 0xbd800000, v10
.LBB0_608:
	s_or_b64 exec, exec, s[52:53]
	v_lshl_add_u32 v48, v45, 8, v19
	s_and_saveexec_b64 s[52:53], s[50:51]
	ds_write_b32 v48, v10
	s_or_b64 exec, exec, s[52:53]
	s_movk_i32 s5, 0x800
	v_add_u32_e32 v47, 32, v21
	v_mov_b32_e32 v12, s29
	v_mov_b32_e32 v10, s29
	v_cmp_gt_i32_e64 s[52:53], s5, v18
	v_mov_b32_e32 v11, 0
	s_and_saveexec_b64 s[54:55], s[52:53]
	s_cbranch_execz .LBB0_612
	v_add_u32_e32 v12, s3, v47
	v_mov_b64_e32 v[10:11], s[64:65]
	v_mad_i64_i32 v[10:11], s[6:7], v12, s76, v[10:11]
	v_lshl_add_u64 v[10:11], v[22:23], 2, v[10:11]
	v_add_co_u32_e32 v10, vcc, 0x3000, v10
	s_mov_b32 s5, 0xbfb8aa3b
	s_nop 0
	v_addc_co_u32_e32 v11, vcc, 0, v11, vcc
	v_mov_b32_e32 v12, v82
	s_mov_b32 s6, 0x3f317218
	v_mov_b32_e32 v10, v83
	v_lshl_add_u32 v11, v47, 6, 0
	ds_read_b128 v[14:17], v11 offset:34816
	ds_read_b128 v[50:53], v11 offset:34832
	ds_read_b128 v[54:57], v11 offset:34848
	ds_read_b128 v[58:61], v11 offset:34864
	s_waitcnt lgkmcnt(3)
	v_fma_f32 v11, v43, v14, v38
	v_fmac_f32_e32 v11, v42, v15
	v_fmac_f32_e32 v11, v41, v16
	v_fmac_f32_e32 v11, v40, v17
	s_waitcnt lgkmcnt(2)
	v_fmac_f32_e32 v11, v44, v50
	v_fmac_f32_e32 v11, v39, v51
	v_pk_mul_f32 v[14:15], v[32:33], v[52:53]
	s_waitcnt vmcnt(1)
	v_mul_f32_e32 v12, 0x3e000000, v12
	v_add_f32_e32 v11, v11, v14
	v_add_f32_e32 v11, v11, v15
	s_waitcnt lgkmcnt(1)
	v_pk_mul_f32 v[14:15], v[30:31], v[54:55]
	s_nop 0
	v_add_f32_e32 v11, v11, v14
	v_add_f32_e32 v11, v11, v15
	v_pk_mul_f32 v[14:15], v[28:29], v[56:57]
	s_nop 0
	v_add_f32_e32 v11, v11, v14
	v_add_f32_e32 v11, v11, v15
	s_waitcnt lgkmcnt(0)
; DI float softplus_(float x) { return fmaxf(x, 0.f) + log1pf(__expf(-fabsf(x))); }
; template <int K, bool HG>
; DI void prep_gla(LAS unsigned char* lds, const Params& P, int l, int unit) {
;     ...
;             else { const int ch = up.h * 64 + k; qv[i] = P32[row * LDP + C_CQ + ch] * 0.125f; kv[i] = P32[row * LDP + C_CK + ch]; float x = bias;
; #pragma unroll
;                 for (int rr = 0; rr < 16; ++rr) x += cl[t * 16 + rr] * wcol[rr];
;                 lg = -softplus_(-x) * (1.f / 16.f); } }
	v_pk_mul_f32 v[14:15], v[24:25], v[58:59]
	s_nop 0
	v_add_f32_e32 v11, v11, v14
	v_add_f32_e32 v11, v11, v15
	v_pk_mul_f32 v[14:15], v[26:27], v[60:61]
	s_nop 0
	v_add_f32_e32 v11, v11, v14
	v_add_f32_e32 v11, v11, v15
	v_max_f32_e64 v13, -v11, 0
	v_mul_f32_e64 v11, |v11|, s5
	v_exp_f32_e32 v11, v11
	s_mov_b32 s5, 0x3f2aaaab
	v_add_f32_e32 v16, 1.0, v11
	v_add_f32_e32 v14, -1.0, v16
	v_sub_f32_e32 v15, v14, v16
	v_add_f32_e32 v15, 1.0, v15
	v_sub_f32_e32 v14, v11, v14
	v_add_f32_e32 v17, v14, v15
	v_frexp_mant_f32_e32 v14, v16
	v_cmp_gt_f32_e32 vcc, s5, v14
	v_cvt_f64_f32_e32 v[14:15], v16
	v_frexp_exp_i32_f64_e32 v14, v[14:15]
	v_subbrev_co_u32_e32 v49, vcc, 0, v14, vcc
	v_sub_u32_e32 v14, 0, v49
	v_ldexp_f32 v15, v16, v14
	v_add_f32_e32 v16, -1.0, v15
	v_add_f32_e32 v50, 1.0, v15
	v_ldexp_f32 v14, v17, v14
	v_add_f32_e32 v17, 1.0, v16
	v_add_f32_e32 v51, -1.0, v50
	v_sub_f32_e32 v17, v15, v17
	v_sub_f32_e32 v15, v15, v51
	v_add_f32_e32 v17, v14, v17
	v_add_f32_e32 v14, v14, v15
	v_add_f32_e32 v54, v50, v14
	v_rcp_f32_e32 v56, v54
	v_sub_f32_e32 v15, v54, v50
	v_sub_f32_e32 v55, v14, v15
	v_add_f32_e32 v15, v16, v17
	v_mul_f32_e32 v58, v15, v56
	v_sub_f32_e32 v14, v15, v16
	v_mul_f32_e32 v16, v54, v58
	v_fma_f32 v50, v58, v54, -v16
	v_fmac_f32_e32 v50, v58, v55
	v_sub_f32_e32 v57, v17, v14
	v_add_f32_e32 v14, v16, v50
	v_sub_f32_e32 v17, v15, v14
	v_pk_add_f32 v[52:53], v[14:15], v[16:17] neg_lo:[0,1] neg_hi:[0,1]
	v_mov_b32_e32 v51, v14
	v_pk_add_f32 v[14:15], v[52:53], v[50:51] neg_lo:[0,1] neg_hi:[0,1]
	s_mov_b32 s5, 0x7f800000
	v_add_f32_e32 v15, v57, v15
	v_add_f32_e32 v14, v14, v15
	v_add_f32_e32 v15, v17, v14
	v_mul_f32_e32 v57, v56, v15
	v_mul_f32_e32 v16, v54, v57
	v_fma_f32 v50, v57, v54, -v16
	v_fmac_f32_e32 v50, v57, v55
	v_sub_f32_e32 v17, v17, v15
	v_add_f32_e32 v54, v14, v17
	v_add_f32_e32 v14, v16, v50
	v_sub_f32_e32 v17, v15, v14
	v_pk_add_f32 v[52:53], v[14:15], v[16:17] neg_lo:[0,1] neg_hi:[0,1]
	v_mov_b32_e32 v51, v14
	v_pk_add_f32 v[14:15], v[52:53], v[50:51] neg_lo:[0,1] neg_hi:[0,1]
	v_cmp_neq_f32_e32 vcc, s5, v11
	v_add_f32_e32 v15, v54, v15
	v_add_f32_e32 v14, v14, v15
	v_add_f32_e32 v15, v58, v57
	v_add_f32_e32 v14, v17, v14
	v_sub_f32_e32 v16, v15, v58
	v_mul_f32_e32 v14, v56, v14
	v_sub_f32_e32 v16, v57, v16
	v_add_f32_e32 v16, v16, v14
	v_add_f32_e32 v50, v15, v16
	v_mul_f32_e32 v51, v50, v50
	v_fmamk_f32 v14, v51, 0x3e9b6dac, v236
	v_fmaak_f32 v199, v51, v14, 0x3f2aaada
	v_cvt_f32_i32_e32 v14, v49
	v_sub_f32_e32 v15, v50, v15
	v_sub_f32_e32 v15, v16, v15
	v_ldexp_f32 v49, v15, 1
	v_mul_f32_e32 v15, v50, v51
	v_ldexp_f32 v17, v50, 1
	v_pk_mul_f32 v[50:51], v[14:15], v[198:199]
	s_mov_b32 s5, 0x33800000
	v_fma_f32 v16, v14, s6, -v50
	v_fmac_f32_e32 v16, 0xb102e308, v14
	v_pk_add_f32 v[14:15], v[50:51], v[16:17]
	v_mov_b32_e32 v52, v50
	v_sub_f32_e32 v17, v15, v17
	v_sub_f32_e32 v17, v51, v17
	v_add_f32_e32 v53, v49, v17
	v_pk_add_f32 v[50:51], v[14:15], v[50:51] neg_lo:[0,1] neg_hi:[0,1]
	v_pk_add_f32 v[54:55], v[14:15], v[52:53]
	v_mov_b32_e32 v17, v14
	v_mov_b32_e32 v51, v55
	v_pk_add_f32 v[56:57], v[16:17], v[50:51] neg_lo:[0,1] neg_hi:[0,1]
	v_pk_add_f32 v[16:17], v[16:17], v[50:51]
	v_mov_b32_e32 v52, v53
	v_pk_add_f32 v[50:51], v[16:17], v[14:15] op_sel:[1,0] op_sel_hi:[0,1] neg_lo:[0,1] neg_hi:[0,1]
	v_pk_add_f32 v[58:59], v[54:55], v[50:51] op_sel_hi:[1,0] neg_lo:[0,1] neg_hi:[0,1]
	v_mov_b32_e32 v54, v55
	v_mov_b32_e32 v55, v17
	v_pk_mov_b32 v[50:51], v[14:15], v[50:51] op_sel:[1,0]
	v_mov_b32_e32 v53, v14
	v_pk_add_f32 v[50:51], v[54:55], v[50:51] neg_lo:[0,1] neg_hi:[0,1]
	v_mov_b32_e32 v58, v56
	v_pk_add_f32 v[14:15], v[52:53], v[50:51] neg_lo:[0,1] neg_hi:[0,1]
	v_mov_b32_e32 v57, v17
	v_pk_add_f32 v[50:51], v[58:59], v[14:15]
	s_nop 0
	v_pk_add_f32 v[52:53], v[50:51], v[50:51] op_sel:[0,1] op_sel_hi:[1,0]
	s_nop 0
	v_pk_add_f32 v[16:17], v[16:17], v[52:53] op_sel:[1,0] op_sel_hi:[0,1]
	v_mov_b32_e32 v51, v16
	v_pk_add_f32 v[54:55], v[50:51], v[56:57] neg_lo:[0,1] neg_hi:[0,1]
	v_mov_b32_e32 v15, v52
	v_sub_f32_e32 v17, v50, v54
	v_pk_add_f32 v[14:15], v[14:15], v[54:55] neg_lo:[0,1] neg_hi:[0,1]
	v_sub_f32_e32 v17, v56, v17
	v_add_f32_e32 v14, v14, v17
	v_add_f32_e32 v14, v14, v15
	v_add_f32_e32 v14, v16, v14
	v_cndmask_b32_e32 v14, v239, v14, vcc
	v_cmp_ngt_f32_e32 vcc, -1.0, v11
	s_nop 1
	v_cndmask_b32_e32 v14, v237, v14, vcc
	v_cmp_neq_f32_e32 vcc, -1.0, v11
	s_nop 1
	v_cndmask_b32_e32 v14, v203, v14, vcc
	v_cmp_lt_f32_e64 vcc, |v11|, s5
	s_nop 1
	v_cndmask_b32_e32 v11, v14, v11, vcc
	v_add_f32_e32 v11, v13, v11
	v_mul_f32_e32 v11, 0xbd800000, v11
; DI float sigm(float x) { return __builtin_amdgcn_rcpf(1.f + __expf(-x)); }
; DI float softplus_(float x) { return fmaxf(x, 0.f) + log1pf(__expf(-fabsf(x))); }
; template <int K, bool HG>
; DI void prep_gla(LAS unsigned char* lds, const Params& P, int l, int unit) {
;     ...
;     for (int i = 0; i < NE; ++i) { const int t = t0 + TS * i; qv[i] = 0.f; kv[i] = 0.f; float lg = 0.f;
;         if (t < up.nvalid) { const size_t row = (size_t)(up.row0 + t);
;             if (HG) { const int ch = up.h * 128 + k; const float fp = P32[row * LDP + C_BF + ch]; qv[i] = P32[row * LDP + C_BQ + ch];
;                 const float f = lb + (1.f - lb) * sigm(fp); lg = __logf(fmaxf(f, 1e-30f)); kv[i] = (1.f - lb) * sigm(-fp); }
;             else { const int ch = up.h * 64 + k; qv[i] = P32[row * LDP + C_CQ + ch] * 0.125f; kv[i] = P32[row * LDP + C_CK + ch]; float x = bias;
; #pragma unroll
;                 for (int rr = 0; rr < 16; ++rr) x += cl[t * 16 + rr] * wcol[rr];
;                 lg = -softplus_(-x) * (1.f / 16.f); } }
;         if (t < TR) Gs[t * K + k] = lg; }
.LBB0_612:
	s_or_b64 exec, exec, s[54:55]
	v_lshl_add_u32 v50, v47, 8, v19
	s_and_saveexec_b64 s[54:55], s[52:53]
	ds_write_b32 v50, v11
	s_or_b64 exec, exec, s[54:55]
	s_movk_i32 s5, 0x600
	v_add_u32_e32 v49, 40, v21
	v_mov_b32_e32 v13, s29
	v_mov_b32_e32 v11, s29
	v_cmp_gt_i32_e64 s[54:55], s5, v18
	v_mov_b32_e32 v14, 0
	s_and_saveexec_b64 s[56:57], s[54:55]
	s_cbranch_execz .LBB0_616
	v_add_u32_e32 v11, s3, v49
	v_mov_b64_e32 v[14:15], s[64:65]
	v_mad_i64_i32 v[14:15], s[6:7], v11, s76, v[14:15]
	v_lshl_add_u64 v[14:15], v[22:23], 2, v[14:15]
	v_add_co_u32_e32 v14, vcc, 0x3000, v14
	v_lshl_add_u32 v51, v49, 6, 0
	s_nop 0
	v_addc_co_u32_e32 v15, vcc, 0, v15, vcc
	v_mov_b32_e32 v11, v84
	s_mov_b32 s5, 0xbfb8aa3b
	s_mov_b32 s6, 0x3f317218
	s_waitcnt vmcnt(0)
	v_mul_f32_e32 v13, 0x3e000000, v11
	v_mov_b32_e32 v11, v85
	ds_read_b128 v[14:17], v51 offset:34816
	ds_read_b128 v[52:55], v51 offset:34832
	ds_read_b128 v[56:59], v51 offset:34848
	ds_read_b128 v[60:63], v51 offset:34864
	s_waitcnt lgkmcnt(3)
	v_fma_f32 v51, v43, v14, v38
	v_fmac_f32_e32 v51, v42, v15
	v_fmac_f32_e32 v51, v41, v16
	v_fmac_f32_e32 v51, v40, v17
	s_waitcnt lgkmcnt(2)
	v_fmac_f32_e32 v51, v44, v52
	v_fmac_f32_e32 v51, v39, v53
	v_pk_mul_f32 v[14:15], v[32:33], v[54:55]
	s_nop 0
	v_add_f32_e32 v14, v51, v14
	v_add_f32_e32 v16, v14, v15
	s_waitcnt lgkmcnt(1)
	v_pk_mul_f32 v[14:15], v[30:31], v[56:57]
	s_nop 0
	v_add_f32_e32 v14, v16, v14
	v_add_f32_e32 v16, v14, v15
	v_pk_mul_f32 v[14:15], v[28:29], v[58:59]
	s_nop 0
	v_add_f32_e32 v14, v16, v14
	v_add_f32_e32 v16, v14, v15
	s_waitcnt lgkmcnt(0)
	v_pk_mul_f32 v[14:15], v[24:25], v[60:61]
	s_nop 0
	v_add_f32_e32 v14, v16, v14
	v_add_f32_e32 v16, v14, v15
	v_pk_mul_f32 v[14:15], v[26:27], v[62:63]
	s_nop 0
	v_add_f32_e32 v14, v16, v14
	v_add_f32_e32 v14, v14, v15
	v_max_f32_e64 v51, -v14, 0
	v_mul_f32_e64 v14, |v14|, s5
	v_exp_f32_e32 v62, v14
	s_mov_b32 s5, 0x3f2aaaab
	v_add_f32_e32 v16, 1.0, v62
	v_add_f32_e32 v14, -1.0, v16
	v_sub_f32_e32 v15, v14, v16
	v_add_f32_e32 v15, 1.0, v15
	v_sub_f32_e32 v14, v62, v14
	v_add_f32_e32 v17, v14, v15
	v_frexp_mant_f32_e32 v14, v16
	v_cmp_gt_f32_e32 vcc, s5, v14
	v_cvt_f64_f32_e32 v[14:15], v16
	v_frexp_exp_i32_f64_e32 v14, v[14:15]
	v_subbrev_co_u32_e32 v56, vcc, 0, v14, vcc
	v_sub_u32_e32 v14, 0, v56
	v_ldexp_f32 v15, v16, v14
	v_add_f32_e32 v16, -1.0, v15
	v_add_f32_e32 v52, 1.0, v15
	v_ldexp_f32 v14, v17, v14
	v_add_f32_e32 v17, 1.0, v16
	v_add_f32_e32 v53, -1.0, v52
	v_sub_f32_e32 v17, v15, v17
	v_sub_f32_e32 v15, v15, v53
	v_add_f32_e32 v17, v14, v17
	v_add_f32_e32 v14, v14, v15
	v_add_f32_e32 v57, v52, v14
	v_rcp_f32_e32 v59, v57
	v_sub_f32_e32 v15, v57, v52
	v_sub_f32_e32 v58, v14, v15
	v_add_f32_e32 v15, v16, v17
	v_mul_f32_e32 v61, v15, v59
	v_sub_f32_e32 v14, v15, v16
	v_mul_f32_e32 v16, v57, v61
	v_fma_f32 v52, v61, v57, -v16
	v_fmac_f32_e32 v52, v61, v58
	v_sub_f32_e32 v60, v17, v14
	v_add_f32_e32 v14, v16, v52
	v_sub_f32_e32 v17, v15, v14
	v_pk_add_f32 v[54:55], v[14:15], v[16:17] neg_lo:[0,1] neg_hi:[0,1]
	v_mov_b32_e32 v53, v14
	v_pk_add_f32 v[14:15], v[54:55], v[52:53] neg_lo:[0,1] neg_hi:[0,1]
	s_mov_b32 s5, 0x7f800000
	v_add_f32_e32 v15, v60, v15
	v_add_f32_e32 v14, v14, v15
	v_add_f32_e32 v15, v17, v14
	v_mul_f32_e32 v60, v59, v15
	v_mul_f32_e32 v16, v57, v60
	v_fma_f32 v52, v60, v57, -v16
	v_fmac_f32_e32 v52, v60, v58
	v_sub_f32_e32 v17, v17, v15
	v_add_f32_e32 v57, v14, v17
	v_add_f32_e32 v14, v16, v52
	v_sub_f32_e32 v17, v15, v14
	v_pk_add_f32 v[54:55], v[14:15], v[16:17] neg_lo:[0,1] neg_hi:[0,1]
	v_mov_b32_e32 v53, v14
	v_pk_add_f32 v[14:15], v[54:55], v[52:53] neg_lo:[0,1] neg_hi:[0,1]
	v_cmp_neq_f32_e32 vcc, s5, v62
	v_add_f32_e32 v15, v57, v15
	v_add_f32_e32 v14, v14, v15
	v_add_f32_e32 v15, v61, v60
	v_add_f32_e32 v14, v17, v14
	v_sub_f32_e32 v16, v15, v61
	v_mul_f32_e32 v14, v59, v14
	v_sub_f32_e32 v16, v60, v16
	v_add_f32_e32 v16, v16, v14
	v_add_f32_e32 v52, v15, v16
	v_mul_f32_e32 v53, v52, v52
	v_fmamk_f32 v14, v53, 0x3e9b6dac, v236
	v_fmaak_f32 v199, v53, v14, 0x3f2aaada
	v_cvt_f32_i32_e32 v14, v56
	v_sub_f32_e32 v15, v52, v15
	v_sub_f32_e32 v15, v16, v15
	v_ldexp_f32 v54, v15, 1
	v_mul_f32_e32 v15, v52, v53
	v_ldexp_f32 v17, v52, 1
	v_pk_mul_f32 v[52:53], v[14:15], v[198:199]
	s_mov_b32 s5, 0x33800000
	v_fma_f32 v16, v14, s6, -v52
	v_fmac_f32_e32 v16, 0xb102e308, v14
	v_pk_add_f32 v[14:15], v[52:53], v[16:17]
	s_nop 0
	v_sub_f32_e32 v17, v15, v17
	v_sub_f32_e32 v17, v53, v17
	v_add_f32_e32 v55, v54, v17
	v_mov_b32_e32 v54, v52
	v_pk_add_f32 v[52:53], v[14:15], v[52:53] neg_lo:[0,1] neg_hi:[0,1]
	v_pk_add_f32 v[56:57], v[14:15], v[54:55]
	v_mov_b32_e32 v17, v14
	v_mov_b32_e32 v53, v57
	v_pk_add_f32 v[58:59], v[16:17], v[52:53] neg_lo:[0,1] neg_hi:[0,1]
	v_pk_add_f32 v[16:17], v[16:17], v[52:53]
	v_mov_b32_e32 v54, v55
	v_pk_add_f32 v[52:53], v[16:17], v[14:15] op_sel:[1,0] op_sel_hi:[0,1] neg_lo:[0,1] neg_hi:[0,1]
	v_pk_add_f32 v[60:61], v[56:57], v[52:53] op_sel_hi:[1,0] neg_lo:[0,1] neg_hi:[0,1]
	v_mov_b32_e32 v56, v57
	v_mov_b32_e32 v57, v17
	v_pk_mov_b32 v[52:53], v[14:15], v[52:53] op_sel:[1,0]
	v_mov_b32_e32 v55, v14
	v_pk_add_f32 v[52:53], v[56:57], v[52:53] neg_lo:[0,1] neg_hi:[0,1]
	v_mov_b32_e32 v60, v58
	v_pk_add_f32 v[14:15], v[54:55], v[52:53] neg_lo:[0,1] neg_hi:[0,1]
	v_mov_b32_e32 v59, v17
	v_pk_add_f32 v[52:53], v[60:61], v[14:15]
	s_nop 0
	v_pk_add_f32 v[54:55], v[52:53], v[52:53] op_sel:[0,1] op_sel_hi:[1,0]
	s_nop 0
	v_pk_add_f32 v[16:17], v[16:17], v[54:55] op_sel:[1,0] op_sel_hi:[0,1]
	v_mov_b32_e32 v53, v16
	v_pk_add_f32 v[56:57], v[52:53], v[58:59] neg_lo:[0,1] neg_hi:[0,1]
	v_mov_b32_e32 v15, v54
	v_sub_f32_e32 v17, v52, v56
	v_pk_add_f32 v[14:15], v[14:15], v[56:57] neg_lo:[0,1] neg_hi:[0,1]
	v_sub_f32_e32 v17, v58, v17
	v_add_f32_e32 v14, v14, v17
	v_add_f32_e32 v14, v14, v15
	v_add_f32_e32 v14, v16, v14
	v_cndmask_b32_e32 v14, v239, v14, vcc
	v_cmp_ngt_f32_e32 vcc, -1.0, v62
	s_nop 1
	v_cndmask_b32_e32 v14, v237, v14, vcc
	v_cmp_neq_f32_e32 vcc, -1.0, v62
	s_nop 1
	v_cndmask_b32_e32 v14, v203, v14, vcc
	v_cmp_lt_f32_e64 vcc, |v62|, s5
	s_nop 1
	v_cndmask_b32_e32 v14, v14, v62, vcc
	v_add_f32_e32 v14, v51, v14
	v_mul_f32_e32 v14, 0xbd800000, v14
; DI float sigm(float x) { return __builtin_amdgcn_rcpf(1.f + __expf(-x)); }
; DI float softplus_(float x) { return fmaxf(x, 0.f) + log1pf(__expf(-fabsf(x))); }
; template <int K, bool HG>
; DI void prep_gla(LAS unsigned char* lds, const Params& P, int l, int unit) {
;     ...
;     for (int i = 0; i < NE; ++i) { const int t = t0 + TS * i; qv[i] = 0.f; kv[i] = 0.f; float lg = 0.f;
;         if (t < up.nvalid) { const size_t row = (size_t)(up.row0 + t);
;             if (HG) { const int ch = up.h * 128 + k; const float fp = P32[row * LDP + C_BF + ch]; qv[i] = P32[row * LDP + C_BQ + ch];
;                 const float f = lb + (1.f - lb) * sigm(fp); lg = __logf(fmaxf(f, 1e-30f)); kv[i] = (1.f - lb) * sigm(-fp); }
;             else { const int ch = up.h * 64 + k; qv[i] = P32[row * LDP + C_CQ + ch] * 0.125f; kv[i] = P32[row * LDP + C_CK + ch]; float x = bias;
; #pragma unroll
;                 for (int rr = 0; rr < 16; ++rr) x += cl[t * 16 + rr] * wcol[rr];
;                 lg = -softplus_(-x) * (1.f / 16.f); } }
;         if (t < TR) Gs[t * K + k] = lg; }
.LBB0_616:
	s_or_b64 exec, exec, s[56:57]
	v_lshl_add_u32 v52, v49, 8, v19
	s_and_saveexec_b64 s[56:57], s[54:55]
	ds_write_b32 v52, v14
	s_or_b64 exec, exec, s[56:57]
	v_add_u32_e32 v51, 48, v21
	v_mov_b32_e32 v16, s29
	v_mov_b32_e32 v14, s29
	v_mov_b32_e32 v15, 0
	s_and_saveexec_b64 s[56:57], s[42:43]
	s_cbranch_execz .LBB0_620
	v_add_u32_e32 v16, s3, v51
	v_mov_b64_e32 v[14:15], s[64:65]
	v_mad_i64_i32 v[14:15], s[6:7], v16, s76, v[14:15]
	v_lshl_add_u64 v[14:15], v[22:23], 2, v[14:15]
	v_add_co_u32_e32 v14, vcc, 0x3000, v14
	s_mov_b32 s5, 0xbfb8aa3b
	s_nop 0
	v_addc_co_u32_e32 v15, vcc, 0, v15, vcc
	v_mov_b32_e32 v16, v86
	s_mov_b32 s6, 0x3f317218
	v_mov_b32_e32 v14, v87
	v_lshl_add_u32 v15, v51, 6, 0
	ds_read_b128 v[54:57], v15 offset:34816
	ds_read_b128 v[58:61], v15 offset:34832
	ds_read_b128 v[62:65], v15 offset:34848
	ds_read_b128 v[66:69], v15 offset:34864
	s_waitcnt lgkmcnt(3)
	v_fma_f32 v15, v43, v54, v38
	v_fmac_f32_e32 v15, v42, v55
	v_fmac_f32_e32 v15, v41, v56
	v_fmac_f32_e32 v15, v40, v57
	s_waitcnt lgkmcnt(2)
	v_fmac_f32_e32 v15, v44, v58
	v_fmac_f32_e32 v15, v39, v59
	v_pk_mul_f32 v[54:55], v[32:33], v[60:61]
	s_waitcnt vmcnt(1)
	v_mul_f32_e32 v16, 0x3e000000, v16
	v_add_f32_e32 v15, v15, v54
	v_add_f32_e32 v15, v15, v55
	s_waitcnt lgkmcnt(1)
	v_pk_mul_f32 v[54:55], v[30:31], v[62:63]
	s_nop 0
	v_add_f32_e32 v15, v15, v54
	v_add_f32_e32 v15, v15, v55
	v_pk_mul_f32 v[54:55], v[28:29], v[64:65]
	s_nop 0
	v_add_f32_e32 v15, v15, v54
	v_add_f32_e32 v15, v15, v55
	s_waitcnt lgkmcnt(0)
	v_pk_mul_f32 v[54:55], v[24:25], v[66:67]
	s_nop 0
	v_add_f32_e32 v15, v15, v54
	v_add_f32_e32 v15, v15, v55
	v_pk_mul_f32 v[54:55], v[26:27], v[68:69]
	s_nop 0
	v_add_f32_e32 v15, v15, v54
	v_add_f32_e32 v15, v15, v55
	v_max_f32_e64 v17, -v15, 0
	v_mul_f32_e64 v15, |v15|, s5
	v_exp_f32_e32 v15, v15
	s_mov_b32 s5, 0x3f2aaaab
	v_add_f32_e32 v53, 1.0, v15
	v_add_f32_e32 v54, -1.0, v53
	v_sub_f32_e32 v55, v54, v53
	v_add_f32_e32 v55, 1.0, v55
	v_sub_f32_e32 v54, v15, v54
	v_add_f32_e32 v56, v54, v55
	v_frexp_mant_f32_e32 v54, v53
	v_cmp_gt_f32_e32 vcc, s5, v54
	v_cvt_f64_f32_e32 v[54:55], v53
	v_frexp_exp_i32_f64_e32 v54, v[54:55]
	v_subbrev_co_u32_e32 v62, vcc, 0, v54, vcc
	v_sub_u32_e32 v54, 0, v62
	v_ldexp_f32 v53, v53, v54
	v_ldexp_f32 v54, v56, v54
	v_add_f32_e32 v56, -1.0, v53
	v_add_f32_e32 v55, 1.0, v56
	v_sub_f32_e32 v55, v53, v55
	v_add_f32_e32 v57, v54, v55
	v_add_f32_e32 v55, 1.0, v53
	v_add_f32_e32 v58, -1.0, v55
	v_sub_f32_e32 v53, v53, v58
	v_add_f32_e32 v53, v54, v53
	v_add_f32_e32 v63, v55, v53
	v_rcp_f32_e32 v64, v63
	v_sub_f32_e32 v54, v63, v55
	v_add_f32_e32 v55, v56, v57
	v_sub_f32_e32 v53, v53, v54
	v_mul_f32_e32 v66, v55, v64
	v_sub_f32_e32 v54, v55, v56
	v_mul_f32_e32 v56, v63, v66
	v_fma_f32 v58, v66, v63, -v56
	v_fmac_f32_e32 v58, v66, v53
	v_sub_f32_e32 v65, v57, v54
	v_add_f32_e32 v54, v56, v58
	v_sub_f32_e32 v57, v55, v54
	v_pk_add_f32 v[60:61], v[54:55], v[56:57] neg_lo:[0,1] neg_hi:[0,1]
	v_mov_b32_e32 v59, v54
	v_pk_add_f32 v[54:55], v[60:61], v[58:59] neg_lo:[0,1] neg_hi:[0,1]
	s_mov_b32 s5, 0x7f800000
	v_add_f32_e32 v55, v65, v55
	v_add_f32_e32 v54, v54, v55
	v_add_f32_e32 v55, v57, v54
	v_mul_f32_e32 v65, v64, v55
	v_mul_f32_e32 v56, v63, v65
	v_fma_f32 v58, v65, v63, -v56
	v_fmac_f32_e32 v58, v65, v53
	v_sub_f32_e32 v53, v57, v55
	v_add_f32_e32 v53, v54, v53
	v_add_f32_e32 v54, v56, v58
	v_sub_f32_e32 v57, v55, v54
	v_pk_add_f32 v[60:61], v[54:55], v[56:57] neg_lo:[0,1] neg_hi:[0,1]
	v_mov_b32_e32 v59, v54
	v_pk_add_f32 v[54:55], v[60:61], v[58:59] neg_lo:[0,1] neg_hi:[0,1]
	v_cmp_neq_f32_e32 vcc, s5, v15
	v_add_f32_e32 v53, v53, v55
	v_add_f32_e32 v53, v54, v53
	v_add_f32_e32 v55, v66, v65
	v_add_f32_e32 v53, v57, v53
	v_sub_f32_e32 v54, v55, v66
	v_mul_f32_e32 v53, v64, v53
	v_sub_f32_e32 v54, v65, v54
	v_add_f32_e32 v53, v54, v53
	v_add_f32_e32 v56, v55, v53
	v_mul_f32_e32 v58, v56, v56
	v_fmamk_f32 v54, v58, 0x3e9b6dac, v236
	v_fmaak_f32 v199, v58, v54, 0x3f2aaada
	v_cvt_f32_i32_e32 v54, v62
	v_sub_f32_e32 v55, v56, v55
	v_sub_f32_e32 v53, v53, v55
	v_mul_f32_e32 v55, v56, v58
	v_pk_mul_f32 v[58:59], v[54:55], v[198:199]
	v_ldexp_f32 v57, v56, 1
	v_fma_f32 v56, v54, s6, -v58
	v_fmac_f32_e32 v56, 0xb102e308, v54
	v_pk_add_f32 v[54:55], v[58:59], v[56:57]
	v_ldexp_f32 v53, v53, 1
	v_sub_f32_e32 v57, v55, v57
	v_sub_f32_e32 v57, v59, v57
	v_add_f32_e32 v61, v53, v57
	v_mov_b32_e32 v60, v58
	v_pk_add_f32 v[58:59], v[54:55], v[58:59] neg_lo:[0,1] neg_hi:[0,1]
	v_pk_add_f32 v[62:63], v[54:55], v[60:61]
	v_mov_b32_e32 v57, v54
	v_mov_b32_e32 v59, v63
	v_pk_add_f32 v[64:65], v[56:57], v[58:59] neg_lo:[0,1] neg_hi:[0,1]
	v_pk_add_f32 v[56:57], v[56:57], v[58:59]
	v_mov_b32_e32 v60, v61
	v_pk_add_f32 v[58:59], v[56:57], v[54:55] op_sel:[1,0] op_sel_hi:[0,1] neg_lo:[0,1] neg_hi:[0,1]
	v_pk_add_f32 v[66:67], v[62:63], v[58:59] op_sel_hi:[1,0] neg_lo:[0,1] neg_hi:[0,1]
	v_mov_b32_e32 v62, v63
	v_mov_b32_e32 v63, v57
	v_pk_mov_b32 v[58:59], v[54:55], v[58:59] op_sel:[1,0]
	v_mov_b32_e32 v61, v54
	v_pk_add_f32 v[58:59], v[62:63], v[58:59] neg_lo:[0,1] neg_hi:[0,1]
	v_mov_b32_e32 v66, v64
	v_pk_add_f32 v[54:55], v[60:61], v[58:59] neg_lo:[0,1] neg_hi:[0,1]
	v_mov_b32_e32 v65, v57
	v_pk_add_f32 v[58:59], v[66:67], v[54:55]
	s_mov_b32 s5, 0x33800000
	v_pk_add_f32 v[60:61], v[58:59], v[58:59] op_sel:[0,1] op_sel_hi:[1,0]
	s_nop 0
	v_pk_add_f32 v[56:57], v[56:57], v[60:61] op_sel:[1,0] op_sel_hi:[0,1]
	v_mov_b32_e32 v59, v56
	v_pk_add_f32 v[62:63], v[58:59], v[64:65] neg_lo:[0,1] neg_hi:[0,1]
	v_mov_b32_e32 v55, v60
	v_sub_f32_e32 v53, v58, v62
	v_pk_add_f32 v[54:55], v[54:55], v[62:63] neg_lo:[0,1] neg_hi:[0,1]
	v_sub_f32_e32 v53, v64, v53
	v_add_f32_e32 v53, v54, v53
	v_add_f32_e32 v53, v53, v55
	v_add_f32_e32 v53, v56, v53
	v_cndmask_b32_e32 v53, v239, v53, vcc
	v_cmp_ngt_f32_e32 vcc, -1.0, v15
	s_nop 1
	v_cndmask_b32_e32 v53, v237, v53, vcc
	v_cmp_neq_f32_e32 vcc, -1.0, v15
	s_nop 1
	v_cndmask_b32_e32 v53, v203, v53, vcc
	v_cmp_lt_f32_e64 vcc, |v15|, s5
	s_nop 1
	v_cndmask_b32_e32 v15, v53, v15, vcc
	v_add_f32_e32 v15, v17, v15
	v_mul_f32_e32 v15, 0xbd800000, v15
; DI float sigm(float x) { return __builtin_amdgcn_rcpf(1.f + __expf(-x)); }
; DI float softplus_(float x) { return fmaxf(x, 0.f) + log1pf(__expf(-fabsf(x))); }
; template <int K, bool HG>
; DI void prep_gla(LAS unsigned char* lds, const Params& P, int l, int unit) {
;     ...
;     for (int i = 0; i < NE; ++i) { const int t = t0 + TS * i; qv[i] = 0.f; kv[i] = 0.f; float lg = 0.f;
;         if (t < up.nvalid) { const size_t row = (size_t)(up.row0 + t);
;             if (HG) { const int ch = up.h * 128 + k; const float fp = P32[row * LDP + C_BF + ch]; qv[i] = P32[row * LDP + C_BQ + ch];
;                 const float f = lb + (1.f - lb) * sigm(fp); lg = __logf(fmaxf(f, 1e-30f)); kv[i] = (1.f - lb) * sigm(-fp); }
;             else { const int ch = up.h * 64 + k; qv[i] = P32[row * LDP + C_CQ + ch] * 0.125f; kv[i] = P32[row * LDP + C_CK + ch]; float x = bias;
; #pragma unroll
;                 for (int rr = 0; rr < 16; ++rr) x += cl[t * 16 + rr] * wcol[rr];
;                 lg = -softplus_(-x) * (1.f / 16.f); } }
;         if (t < TR) Gs[t * K + k] = lg; }
.LBB0_620:
	s_or_b64 exec, exec, s[56:57]
	v_lshl_add_u32 v54, v51, 8, v19
	s_and_saveexec_b64 s[56:57], s[42:43]
	ds_write_b32 v54, v15
	s_or_b64 exec, exec, s[56:57]
	s_movk_i32 s5, 0x200
	v_add_u32_e32 v53, 56, v21
	v_mov_b32_e32 v17, s29
	v_mov_b32_e32 v15, s29
	v_cmp_gt_i32_e64 s[56:57], s5, v18
	v_mov_b32_e32 v55, 0
	s_and_saveexec_b64 s[66:67], s[56:57]
	s_cbranch_execz .LBB0_624
	v_add_u32_e32 v15, s3, v53
	v_mov_b64_e32 v[56:57], s[64:65]
	v_mad_i64_i32 v[56:57], s[6:7], v15, s76, v[56:57]
	v_lshl_add_u64 v[22:23], v[22:23], 2, v[56:57]
	v_add_co_u32_e32 v22, vcc, 0x3000, v22
	v_lshl_add_u32 v15, v53, 6, 0
	s_nop 0
	v_addc_co_u32_e32 v23, vcc, 0, v23, vcc
	v_mov_b32_e32 v17, v88
	ds_read_b128 v[56:59], v15 offset:34816
	ds_read_b128 v[60:63], v15 offset:34832
	ds_read_b128 v[64:67], v15 offset:34848
	ds_read_b128 v[68:71], v15 offset:34864
	s_mov_b32 s3, 0xbfb8aa3b
	s_waitcnt lgkmcnt(3)
	v_fmac_f32_e32 v38, v43, v56
	v_fmac_f32_e32 v38, v42, v57
	v_fmac_f32_e32 v38, v41, v58
	v_fmac_f32_e32 v38, v40, v59
	s_waitcnt lgkmcnt(2)
	v_fmac_f32_e32 v38, v44, v60
	v_fmac_f32_e32 v38, v39, v61
	v_pk_mul_f32 v[32:33], v[32:33], v[62:63]
	s_waitcnt lgkmcnt(1)
	v_pk_mul_f32 v[30:31], v[30:31], v[64:65]
	v_add_f32_e32 v15, v38, v32
	v_add_f32_e32 v15, v15, v33
	v_add_f32_e32 v15, v15, v30
	v_add_f32_e32 v15, v15, v31
	v_pk_mul_f32 v[28:29], v[28:29], v[66:67]
	s_waitcnt lgkmcnt(0)
	v_pk_mul_f32 v[24:25], v[24:25], v[68:69]
	v_add_f32_e32 v15, v15, v28
	v_add_f32_e32 v15, v15, v29
	v_add_f32_e32 v15, v15, v24
	v_add_f32_e32 v15, v15, v25
	v_pk_mul_f32 v[24:25], v[26:27], v[70:71]
	s_mov_b32 s6, 0x3f317218
	v_add_f32_e32 v15, v15, v24
	v_add_f32_e32 v24, v15, v25
	v_mul_f32_e64 v15, |v24|, s3
	v_exp_f32_e32 v40, v15
	v_mov_b32_e32 v15, v89
	v_max_f32_e64 v41, -v24, 0
	s_mov_b32 s3, 0x3f2aaaab
	v_add_f32_e32 v24, 1.0, v40
	v_add_f32_e32 v25, -1.0, v24
	v_frexp_mant_f32_e32 v26, v24
	v_cvt_f64_f32_e32 v[22:23], v24
	v_sub_f32_e32 v27, v25, v24
	v_frexp_exp_i32_f64_e32 v22, v[22:23]
	v_cmp_gt_f32_e32 vcc, s3, v26
	v_sub_f32_e32 v25, v40, v25
	v_add_f32_e32 v23, 1.0, v27
	v_subbrev_co_u32_e32 v30, vcc, 0, v22, vcc
	v_add_f32_e32 v22, v25, v23
	v_sub_u32_e32 v23, 0, v30
	v_ldexp_f32 v24, v24, v23
	v_add_f32_e32 v25, -1.0, v24
	v_add_f32_e32 v26, 1.0, v24
	v_ldexp_f32 v22, v22, v23
	v_add_f32_e32 v23, 1.0, v25
	v_add_f32_e32 v27, -1.0, v26
	v_sub_f32_e32 v23, v24, v23
	v_sub_f32_e32 v24, v24, v27
	v_add_f32_e32 v27, v22, v23
	v_add_f32_e32 v22, v22, v24
	v_add_f32_e32 v28, v26, v22
	v_rcp_f32_e32 v31, v28
	v_add_f32_e32 v23, v25, v27
	v_sub_f32_e32 v24, v28, v26
	v_sub_f32_e32 v29, v22, v24
	v_mul_f32_e32 v33, v23, v31
	v_mul_f32_e32 v24, v28, v33
	v_fma_f32 v26, v33, v28, -v24
	v_fmac_f32_e32 v26, v33, v29
	v_sub_f32_e32 v25, v23, v25
	v_add_f32_e32 v22, v24, v26
	v_sub_f32_e32 v32, v27, v25
	v_sub_f32_e32 v25, v23, v22
	v_mov_b32_e32 v27, v22
	v_pk_add_f32 v[22:23], v[22:23], v[24:25] neg_lo:[0,1] neg_hi:[0,1]
	s_mov_b32 s3, 0x7f800000
	v_pk_add_f32 v[22:23], v[22:23], v[26:27] neg_lo:[0,1] neg_hi:[0,1]
	v_cmp_neq_f32_e32 vcc, s3, v40
	v_add_f32_e32 v23, v32, v23
	v_add_f32_e32 v22, v22, v23
	v_add_f32_e32 v23, v25, v22
	v_mul_f32_e32 v32, v31, v23
	v_mul_f32_e32 v24, v28, v32
	v_fma_f32 v26, v32, v28, -v24
	v_fmac_f32_e32 v26, v32, v29
	v_sub_f32_e32 v25, v25, v23
	v_add_f32_e32 v38, v22, v25
	v_add_f32_e32 v22, v24, v26
	v_sub_f32_e32 v25, v23, v22
	v_pk_add_f32 v[28:29], v[22:23], v[24:25] neg_lo:[0,1] neg_hi:[0,1]
	v_mov_b32_e32 v27, v22
	v_pk_add_f32 v[22:23], v[28:29], v[26:27] neg_lo:[0,1] neg_hi:[0,1]
	s_mov_b32 s3, 0x33800000
	v_add_f32_e32 v23, v38, v23
	v_add_f32_e32 v22, v22, v23
	v_add_f32_e32 v23, v33, v32
	v_add_f32_e32 v22, v25, v22
	v_sub_f32_e32 v24, v23, v33
	v_mul_f32_e32 v22, v31, v22
	v_sub_f32_e32 v24, v32, v24
	v_add_f32_e32 v24, v24, v22
	v_add_f32_e32 v26, v23, v24
	v_mul_f32_e32 v27, v26, v26
	v_fmamk_f32 v22, v27, 0x3e9b6dac, v236
	v_fmaak_f32 v199, v27, v22, 0x3f2aaada
	v_cvt_f32_i32_e32 v22, v30
	v_sub_f32_e32 v23, v26, v23
	v_sub_f32_e32 v23, v24, v23
	v_ldexp_f32 v28, v23, 1
	v_mul_f32_e32 v23, v26, v27
	v_ldexp_f32 v25, v26, 1
	v_pk_mul_f32 v[26:27], v[22:23], v[198:199]
	s_waitcnt vmcnt(1)
	v_mul_f32_e32 v17, 0x3e000000, v17
	v_fma_f32 v24, v22, s6, -v26
	v_fmac_f32_e32 v24, 0xb102e308, v22
	v_pk_add_f32 v[22:23], v[26:27], v[24:25]
	s_nop 0
	v_sub_f32_e32 v25, v23, v25
	v_sub_f32_e32 v25, v27, v25
	v_add_f32_e32 v29, v28, v25
	v_mov_b32_e32 v28, v26
	v_pk_add_f32 v[26:27], v[22:23], v[26:27] neg_lo:[0,1] neg_hi:[0,1]
	v_pk_add_f32 v[30:31], v[22:23], v[28:29]
	v_mov_b32_e32 v25, v22
	v_mov_b32_e32 v27, v31
	v_pk_add_f32 v[32:33], v[24:25], v[26:27] neg_lo:[0,1] neg_hi:[0,1]
	v_pk_add_f32 v[24:25], v[24:25], v[26:27]
	v_mov_b32_e32 v28, v29
	v_pk_add_f32 v[26:27], v[24:25], v[22:23] op_sel:[1,0] op_sel_hi:[0,1] neg_lo:[0,1] neg_hi:[0,1]
	v_pk_add_f32 v[38:39], v[30:31], v[26:27] op_sel_hi:[1,0] neg_lo:[0,1] neg_hi:[0,1]
	v_mov_b32_e32 v30, v31
	v_mov_b32_e32 v31, v25
	v_pk_mov_b32 v[26:27], v[22:23], v[26:27] op_sel:[1,0]
	v_mov_b32_e32 v29, v22
	v_pk_add_f32 v[26:27], v[30:31], v[26:27] neg_lo:[0,1] neg_hi:[0,1]
	v_mov_b32_e32 v38, v32
	v_pk_add_f32 v[22:23], v[28:29], v[26:27] neg_lo:[0,1] neg_hi:[0,1]
	v_mov_b32_e32 v33, v25
	v_pk_add_f32 v[26:27], v[38:39], v[22:23]
	s_nop 0
	v_pk_add_f32 v[28:29], v[26:27], v[26:27] op_sel:[0,1] op_sel_hi:[1,0]
	s_nop 0
	v_pk_add_f32 v[24:25], v[24:25], v[28:29] op_sel:[1,0] op_sel_hi:[0,1]
	v_mov_b32_e32 v27, v24
	v_pk_add_f32 v[30:31], v[26:27], v[32:33] neg_lo:[0,1] neg_hi:[0,1]
	v_mov_b32_e32 v23, v28
	v_sub_f32_e32 v25, v26, v30
	v_pk_add_f32 v[22:23], v[22:23], v[30:31] neg_lo:[0,1] neg_hi:[0,1]
	v_sub_f32_e32 v25, v32, v25
	v_add_f32_e32 v22, v22, v25
	v_add_f32_e32 v22, v22, v23
	v_add_f32_e32 v22, v24, v22
	v_cndmask_b32_e32 v22, v239, v22, vcc
	v_cmp_ngt_f32_e32 vcc, -1.0, v40
	s_nop 1
	v_cndmask_b32_e32 v22, v237, v22, vcc
	v_cmp_neq_f32_e32 vcc, -1.0, v40
	s_nop 1
	v_cndmask_b32_e32 v22, v203, v22, vcc
	v_cmp_lt_f32_e64 vcc, |v40|, s3
	s_nop 1
	v_cndmask_b32_e32 v22, v22, v40, vcc
	v_add_f32_e32 v22, v41, v22
	v_mul_f32_e32 v55, 0xbd800000, v22
